# grid barriers: the acquire L1 invalidate (buffer_inv sc1) is issued on arrival, right behind the arrival atomic, instead of after the release is observed; nothing can allocate in this CU's L1 in betwe
# speedup vs baseline: 1.0085x; 1.0060x over previous
.LBB0_70:
	s_mov_b64 s[38:39], exec
	v_mbcnt_lo_u32_b32 v1, s38, 0
	v_mbcnt_hi_u32_b32 v1, s39, v1
	v_cmp_eq_u32_e32 vcc, 0, v1
	s_and_saveexec_b64 s[36:37], vcc
	s_cbranch_execz .LBB0_72
	s_bcnt1_i32_b64 s22, s[38:39]
	v_mov_b32_e32 v3, 0
	v_mov_b32_e32 v4, s22
	global_atomic_add v3, v3, v4, s[94:95] sc0
	buffer_inv sc1
.LBB0_72:
	s_or_b64 exec, exec, s[36:37]
	v_cvt_f32_u32_e32 v4, v2
	s_waitcnt vmcnt(1)
	v_readfirstlane_b32 s22, v3
	v_sub_u32_e32 v3, 0, v2
	v_rcp_iflag_f32_e32 v4, v4
	v_add_u32_e32 v5, s22, v1
	v_mul_f32_e32 v4, 0x4f7ffffe, v4
	v_cvt_u32_f32_e32 v4, v4
	v_mul_lo_u32 v1, v3, v4
	v_mul_hi_u32 v1, v4, v1
	v_add_u32_e32 v1, v4, v1
	v_mul_hi_u32 v1, v5, v1
	v_mul_lo_u32 v3, v1, v2
	v_sub_u32_e32 v3, v5, v3
	v_add_u32_e32 v4, 1, v1
	v_cmp_ge_u32_e32 vcc, v3, v2
	s_nop 1
	v_cndmask_b32_e32 v1, v1, v4, vcc
	v_sub_u32_e32 v4, v3, v2
	v_cndmask_b32_e32 v3, v3, v4, vcc
	v_add_u32_e32 v4, 1, v1
	v_cmp_ge_u32_e32 vcc, v3, v2
	v_add_u32_e32 v3, 1, v5
	s_nop 0
	v_cndmask_b32_e32 v1, v1, v4, vcc
	v_mul_lo_u32 v4, v2, v1
	v_add_u32_e32 v2, v4, v2
	v_cmp_ne_u32_e32 vcc, v3, v2
	s_and_saveexec_b64 s[22:23], vcc
	s_xor_b64 s[36:37], exec, s[22:23]
	s_cbranch_execz .LBB0_86
	s_waitcnt lgkmcnt(0)
	v_mov_b32_e32 v0, 0
	global_load_dword v2, v0, s[14:15] sc1
	s_waitcnt vmcnt(0)
	v_cmp_eq_u32_e32 vcc, v2, v1
	s_and_saveexec_b64 s[38:39], vcc
	s_cbranch_execz .LBB0_85
	s_mov_b32 s22, 1
	s_mov_b64 s[40:41], 0
	s_branch .LBB0_76

.LBB0_85:
	s_or_b64 exec, exec, s[38:39]
	s_waitcnt vmcnt(0)
	s_waitcnt vmcnt(0)

.LBB0_103:
	s_or_b64 exec, exec, s[36:37]
	s_mov_b64 s[36:37], exec
	v_mbcnt_lo_u32_b32 v0, s36, 0
	v_mbcnt_hi_u32_b32 v0, s37, v0
	v_cmp_eq_u32_e32 vcc, 0, v0
	s_waitcnt vmcnt(0)
	s_and_saveexec_b64 s[38:39], vcc
	s_cbranch_execz .LBB0_105
	s_bcnt1_i32_b64 s22, s[36:37]
	v_mov_b32_e32 v0, 0
	v_mov_b32_e32 v1, s22
	global_atomic_add v0, v1, s[8:9]

.LBB0_1080:
	s_mov_b64 s[16:17], exec
	v_mbcnt_lo_u32_b32 v1, s16, 0
	v_mbcnt_hi_u32_b32 v1, s17, v1
	v_cmp_eq_u32_e32 vcc, 0, v1
	s_and_saveexec_b64 s[12:13], vcc
	s_cbranch_execz .LBB0_1082
	s_bcnt1_i32_b64 s16, s[16:17]
	v_mov_b32_e32 v3, 0
	v_mov_b32_e32 v4, s16
	global_atomic_add v3, v3, v4, s[94:95] sc0
	buffer_inv sc1
.LBB0_1082:
	s_or_b64 exec, exec, s[12:13]
	v_cvt_f32_u32_e32 v4, v2
	s_waitcnt vmcnt(1)
	v_readfirstlane_b32 s12, v3
	v_sub_u32_e32 v3, 0, v2
	v_rcp_iflag_f32_e32 v4, v4
	v_add_u32_e32 v5, s12, v1
	v_mul_f32_e32 v4, 0x4f7ffffe, v4
	v_cvt_u32_f32_e32 v4, v4
	v_mul_lo_u32 v1, v3, v4
	v_mul_hi_u32 v1, v4, v1
	v_add_u32_e32 v1, v4, v1
	v_mul_hi_u32 v1, v5, v1
	v_mul_lo_u32 v3, v1, v2
	v_sub_u32_e32 v3, v5, v3
	v_add_u32_e32 v4, 1, v1
	v_cmp_ge_u32_e32 vcc, v3, v2
	s_nop 1
	v_cndmask_b32_e32 v1, v1, v4, vcc
	v_sub_u32_e32 v4, v3, v2
	v_cndmask_b32_e32 v3, v3, v4, vcc
	v_add_u32_e32 v4, 1, v1
	v_cmp_ge_u32_e32 vcc, v3, v2
	v_add_u32_e32 v3, 1, v5
	s_nop 0
	v_cndmask_b32_e32 v1, v1, v4, vcc
	v_mul_lo_u32 v4, v2, v1
	v_add_u32_e32 v2, v4, v2
	v_cmp_ne_u32_e32 vcc, v3, v2
	s_and_saveexec_b64 s[12:13], vcc
	s_xor_b64 s[12:13], exec, s[12:13]
	s_cbranch_execz .LBB0_1096
	s_waitcnt lgkmcnt(0)
	v_mov_b32_e32 v0, 0
	global_load_dword v2, v0, s[14:15] sc1
	s_waitcnt vmcnt(0)
	v_cmp_eq_u32_e32 vcc, v2, v1
	s_and_saveexec_b64 s[16:17], vcc
	s_cbranch_execz .LBB0_1095
	s_mov_b32 s22, 1
	s_mov_b64 s[18:19], 0
	s_branch .LBB0_1086

.LBB0_1095:
	s_or_b64 exec, exec, s[16:17]
	s_waitcnt vmcnt(0)
	s_waitcnt vmcnt(0)

.LBB0_1113:
	s_or_b64 exec, exec, s[12:13]
	s_mov_b64 s[12:13], exec
	v_mbcnt_lo_u32_b32 v0, s12, 0
	v_mbcnt_hi_u32_b32 v0, s13, v0
	v_cmp_eq_u32_e32 vcc, 0, v0
	s_waitcnt vmcnt(0)
	s_and_saveexec_b64 s[16:17], vcc
	s_cbranch_execz .LBB0_1115
	s_bcnt1_i32_b64 s12, s[12:13]
	v_mov_b32_e32 v0, 0
	v_mov_b32_e32 v1, s12
	global_atomic_add v0, v1, s[8:9]

.LBB0_1187:
	s_or_b64 exec, exec, s[12:13]
	v_cvt_f32_u32_e32 v4, v2
	s_waitcnt vmcnt(1)
	v_readfirstlane_b32 s12, v3
	v_sub_u32_e32 v3, 0, v2
	v_rcp_iflag_f32_e32 v4, v4
	v_add_u32_e32 v5, s12, v1
	v_mul_f32_e32 v4, 0x4f7ffffe, v4
	v_cvt_u32_f32_e32 v4, v4
	v_mul_lo_u32 v1, v3, v4
	v_mul_hi_u32 v1, v4, v1
	v_add_u32_e32 v1, v4, v1
	v_mul_hi_u32 v1, v5, v1
	v_mul_lo_u32 v3, v1, v2
	v_sub_u32_e32 v3, v5, v3
	v_add_u32_e32 v4, 1, v1
	v_cmp_ge_u32_e32 vcc, v3, v2
	s_nop 1
	v_cndmask_b32_e32 v1, v1, v4, vcc
	v_sub_u32_e32 v4, v3, v2
	v_cndmask_b32_e32 v3, v3, v4, vcc
	v_add_u32_e32 v4, 1, v1
	v_cmp_ge_u32_e32 vcc, v3, v2
	v_add_u32_e32 v3, 1, v5
	s_nop 0
	v_cndmask_b32_e32 v1, v1, v4, vcc
	v_mul_lo_u32 v4, v2, v1
	v_add_u32_e32 v2, v4, v2
	v_cmp_ne_u32_e32 vcc, v3, v2
	s_and_saveexec_b64 s[12:13], vcc
	s_xor_b64 s[12:13], exec, s[12:13]
	s_cbranch_execz .LBB0_1201
	s_waitcnt lgkmcnt(0)
	v_mov_b32_e32 v0, 0
	global_load_dword v2, v0, s[14:15] sc1
	s_waitcnt vmcnt(0)
	v_cmp_eq_u32_e32 vcc, v2, v1
	s_and_saveexec_b64 s[16:17], vcc
	s_cbranch_execz .LBB0_1200
	s_mov_b32 s23, 1
	s_mov_b64 s[18:19], 0
	s_branch .LBB0_1191

.LBB0_1240:
	s_mov_b64 s[18:19], exec
	v_mbcnt_lo_u32_b32 v1, s18, 0
	v_mbcnt_hi_u32_b32 v1, s19, v1
	v_cmp_eq_u32_e32 vcc, 0, v1
	s_and_saveexec_b64 s[16:17], vcc
	s_cbranch_execz .LBB0_1242
	s_bcnt1_i32_b64 s18, s[18:19]
	v_mov_b32_e32 v3, 0
	v_mov_b32_e32 v4, s18
	global_atomic_add v3, v3, v4, s[94:95] sc0
	buffer_inv sc1
.LBB0_1242:
	s_or_b64 exec, exec, s[16:17]
	v_cvt_f32_u32_e32 v4, v2
	s_waitcnt vmcnt(1)
	v_readfirstlane_b32 s16, v3
	v_sub_u32_e32 v3, 0, v2
	v_rcp_iflag_f32_e32 v4, v4
	v_add_u32_e32 v5, s16, v1
	v_mul_f32_e32 v4, 0x4f7ffffe, v4
	v_cvt_u32_f32_e32 v4, v4
	v_mul_lo_u32 v1, v3, v4
	v_mul_hi_u32 v1, v4, v1
	v_add_u32_e32 v1, v4, v1
	v_mul_hi_u32 v1, v5, v1
	v_mul_lo_u32 v3, v1, v2
	v_sub_u32_e32 v3, v5, v3
	v_add_u32_e32 v4, 1, v1
	v_cmp_ge_u32_e32 vcc, v3, v2
	s_nop 1
	v_cndmask_b32_e32 v1, v1, v4, vcc
	v_sub_u32_e32 v4, v3, v2
	v_cndmask_b32_e32 v3, v3, v4, vcc
	v_add_u32_e32 v4, 1, v1
	v_cmp_ge_u32_e32 vcc, v3, v2
	v_add_u32_e32 v3, 1, v5
	s_nop 0
	v_cndmask_b32_e32 v1, v1, v4, vcc
	v_mul_lo_u32 v4, v2, v1
	v_add_u32_e32 v2, v4, v2
	v_cmp_ne_u32_e32 vcc, v3, v2
	s_and_saveexec_b64 s[16:17], vcc
	s_xor_b64 s[16:17], exec, s[16:17]
	s_cbranch_execz .LBB0_1256
	s_waitcnt lgkmcnt(0)
	v_mov_b32_e32 v0, 0
	global_load_dword v2, v0, s[14:15] sc1
	s_waitcnt vmcnt(0)
	v_cmp_eq_u32_e32 vcc, v2, v1
	s_and_saveexec_b64 s[18:19], vcc
	s_cbranch_execz .LBB0_1255
	s_mov_b32 s22, 1
	s_mov_b64 s[36:37], 0
	s_branch .LBB0_1246

.LBB0_1255:
	s_or_b64 exec, exec, s[18:19]
	s_waitcnt vmcnt(0)
	s_waitcnt vmcnt(0)

.LBB0_1273:
	s_or_b64 exec, exec, s[16:17]
	s_mov_b64 s[16:17], exec
	v_mbcnt_lo_u32_b32 v0, s16, 0
	v_mbcnt_hi_u32_b32 v0, s17, v0
	v_cmp_eq_u32_e32 vcc, 0, v0
	s_waitcnt vmcnt(0)
	s_and_saveexec_b64 s[18:19], vcc
	s_cbranch_execz .LBB0_1275
	s_bcnt1_i32_b64 s16, s[16:17]
	v_mov_b32_e32 v0, 0
	v_mov_b32_e32 v1, s16
	global_atomic_add v0, v1, s[8:9]

.LBB0_1302:
	s_waitcnt vmcnt(0)
	s_barrier
	s_and_saveexec_b64 s[4:5], s[92:93]
	s_cbranch_execz .LBB0_1354
	s_add_u32 s12, s88, 0x4000
	s_addc_u32 s13, s89, 0
	v_mov_b32_e32 v0, 0
	global_load_dword v2, v0, s[12:13] offset:3072 sc1
	s_and_b32 s0, s2, 7
	s_lshl_b32 s0, s0, 7
	v_mov_b32_e32 v3, s0
	v_mov_b32_e32 v4, 1
	s_waitcnt vmcnt(0)
	v_readfirstlane_b32 s32, v2
	s_nop 3
	s_cmp_lg_u32 s32, 0
	s_cbranch_scc1 .Lgb6_slow
	global_atomic_add v3, v4, s[12:13] offset:2048
	buffer_inv sc1
	s_mov_b32 s0, 0

.Lgb6_done:
	s_waitcnt vmcnt(0)
	s_branch .LBB0_1354

.LBB0_1318:
	s_mov_b64 s[12:13], exec
	v_mbcnt_lo_u32_b32 v1, s12, 0
	v_mbcnt_hi_u32_b32 v1, s13, v1
	v_cmp_eq_u32_e32 vcc, 0, v1
	s_and_saveexec_b64 s[0:1], vcc
	s_cbranch_execz .LBB0_1320
	s_bcnt1_i32_b64 s3, s[12:13]
	v_mov_b32_e32 v3, 0
	v_mov_b32_e32 v4, s3
	global_atomic_add v3, v3, v4, s[94:95] sc0
	buffer_inv sc1
.LBB0_1320:
	s_or_b64 exec, exec, s[0:1]
	v_cvt_f32_u32_e32 v4, v2
	s_waitcnt vmcnt(1)
	v_readfirstlane_b32 s0, v3
	v_sub_u32_e32 v3, 0, v2
	v_rcp_iflag_f32_e32 v4, v4
	v_add_u32_e32 v5, s0, v1
	v_mul_f32_e32 v4, 0x4f7ffffe, v4
	v_cvt_u32_f32_e32 v4, v4
	v_mul_lo_u32 v1, v3, v4
	v_mul_hi_u32 v1, v4, v1
	v_add_u32_e32 v1, v4, v1
	v_mul_hi_u32 v1, v5, v1
	v_mul_lo_u32 v3, v1, v2
	v_sub_u32_e32 v3, v5, v3
	v_add_u32_e32 v4, 1, v1
	v_cmp_ge_u32_e32 vcc, v3, v2
	s_nop 1
	v_cndmask_b32_e32 v1, v1, v4, vcc
	v_sub_u32_e32 v4, v3, v2
	v_cndmask_b32_e32 v3, v3, v4, vcc
	v_add_u32_e32 v4, 1, v1
	v_cmp_ge_u32_e32 vcc, v3, v2
	v_add_u32_e32 v3, 1, v5
	s_nop 0
	v_cndmask_b32_e32 v1, v1, v4, vcc
	v_mul_lo_u32 v4, v2, v1
	v_add_u32_e32 v2, v4, v2
	v_cmp_ne_u32_e32 vcc, v3, v2
	s_and_saveexec_b64 s[0:1], vcc
	s_xor_b64 s[0:1], exec, s[0:1]
	s_cbranch_execz .LBB0_1334
	s_waitcnt lgkmcnt(0)
	v_mov_b32_e32 v0, 0
	global_load_dword v2, v0, s[14:15] sc1
	s_waitcnt vmcnt(0)
	v_cmp_eq_u32_e32 vcc, v2, v1
	s_and_saveexec_b64 s[12:13], vcc
	s_cbranch_execz .LBB0_1333
	s_mov_b32 s3, 1
	s_mov_b64 s[16:17], 0
	s_branch .LBB0_1324

.LBB0_1333:
	s_or_b64 exec, exec, s[12:13]
	s_waitcnt vmcnt(0)
	s_waitcnt vmcnt(0)

.LBB0_1351:
	s_or_b64 exec, exec, s[0:1]
	s_mov_b64 s[0:1], exec
	v_mbcnt_lo_u32_b32 v0, s0, 0
	v_mbcnt_hi_u32_b32 v0, s1, v0
	v_cmp_eq_u32_e32 vcc, 0, v0
	s_waitcnt vmcnt(0)
	s_and_saveexec_b64 s[6:7], vcc
	s_cbranch_execz .LBB0_1353
	s_bcnt1_i32_b64 s0, s[0:1]
	v_mov_b32_e32 v0, 0
	v_mov_b32_e32 v1, s0
	global_atomic_add v0, v1, s[8:9]
